# dilated sliding-window item hand-written: 5 uniform 32-key blocks per wave, block-skip of the range mask, each workgroup walks adjacent query blocks and keeps the shared K/V tiles in LDS
# speedup vs baseline: 1.0092x; 1.0092x over previous
; DI void phase_local(KP p, int layer, u16* sm) {
;   constexpr int N_DIL = 2304, N_NA = 768, N_KM = 256;
;   for (int it = blockIdx.x; it < N_DIL + N_NA + N_KM; it += gridDim.x) {
;     __syncthreads();
;     if (it < N_DIL) swin_attn_item(p, (it & 7) * (N_DIL / 8) + (it >> 3), sm);
;     else if (it < N_DIL + N_NA) { const int j = it - N_DIL; na_attn_item(p, layer, (j & 7) * (N_NA / 8) + (j >> 3), sm); }
;     else kmax_item(p, layer, it - N_DIL - N_NA);
;   }
.LBB0_260:
	s_or_b64 exec, exec, s[16:17]
	v_readlane_b32 s6, v254, 2
	v_readlane_b32 s7, v254, 3
	s_mov_b64 s[16:17], s[82:83]
	s_andn2_b64 vcc, exec, s[6:7]
	s_waitcnt lgkmcnt(0)
	s_barrier
	s_cbranch_vccnz .LBB0_400
	s_load_dwordx2 s[6:7], s[16:17], 0xb0
	s_load_dwordx4 s[76:79], s[16:17], 0xc8
	s_load_dwordx2 s[28:29], s[16:17], 0x40
	s_load_dwordx2 s[30:31], s[16:17], 0xf0
	s_load_dwordx2 s[34:35], s[16:17], 0xe0
	s_lshl_b32 s12, s22, 4
	s_lshl_b64 s[18:19], s[12:13], 2
	s_waitcnt lgkmcnt(0)
	s_add_u32 s26, s6, s18
	s_addc_u32 s27, s7, s19
	s_mov_b32 s23, s2
	s_branch .LBB0_264
.LBB0_263:
	s_add_i32 s23, s23, s74
	s_cmpk_lt_i32 s23, 0xd00
	s_cbranch_scc0 .LBB0_400

; DI int otid() { int t = threadIdx.x; asm volatile("" : "+v"(t)); return t; }
; DI void swin_attn_item(KP p, int item, u16* sm) {
;   const int tid = otid(), lane = tid & 63, w = __builtin_amdgcn_readfirstlane(tid >> 6), r = lane & 31, hh = lane >> 5;
;   u16* Ks = sm; u16* Vs = sm + 4 * KS_BUF;
;   const int bhp = item >> 6, sub = item & 63;
;   const int pat = bhp % 3, bh = bhp / 3, head = bh % 6, b = bh / 6;
;   const int sh = 2 * pat, L = S >> sh;
;   const int cls = sub >> (6 - sh), pb = sub & ((64 >> sh) - 1);
;   const int P = pb * 256;
;   const int qp = P + 32 * w + r, tq = cls + (qp << sh);
;   const u16* prow = p.proj + (size_t)b * S * NPROJ;
;   bf16x8 qf[4];
; #pragma unroll
;   for (int s = 0; s < 4; ++s) qf[s] = *(const bf16x8*)(prow + (size_t)tq * NPROJ + 768 + head * 64 + s * 16 + 8 * hh);
;   f32x16 O[2];
; #pragma unroll
;   for (int mb = 0; mb < 2; ++mb)
; #pragma unroll
;     for (int i = 0; i < 16; ++i) O[mb][i] = 0.f;
;   float m_run = -1e20f, l_run = 0.f;
;   const int key0 = tid >> 3, ch = tid & 7;
;   const u16* kg = prow + 1152 + head * 64 + ch * 8;
;   auto gk = [&](int j) __attribute__((always_inline)) -> const u16* {
;     int kp = P - 64 + 64 * j + key0; kp = kp < 0 ? 0 : (kp > L - 1 ? L - 1 : kp);
;     return kg + (size_t)(cls + (kp << sh)) * NPROJ;
;   };
;   const uint4 k0 = *(const uint4*)gk(0), v0 = *(const uint4*)(gk(0) + 384), k1 = *(const uint4*)gk(1), v1 = *(const uint4*)(gk(1) + 384);
;   const uint4 k2 = *(const uint4*)gk(2), v2 = *(const uint4*)(gk(2) + 384), k3 = *(const uint4*)gk(3), v3 = *(const uint4*)(gk(3) + 384);
;   const uint4 k4 = *(const uint4*)gk(4), v4 = *(const uint4*)(gk(4) + 384), k5 = *(const uint4*)gk(5), v5 = *(const uint4*)(gk(5) + 384);
;   auto lstore = [&](int buf, const uint4& kr, const uint4& vr) __attribute__((always_inline)) {
;     *(uint4*)(Ks + buf * KS_BUF + key0 * KS_STRIDE + ch * 8) = kr;
;     *(uint4*)(Vs + buf * VS_BUF + key0 * VROW + ch * 8) = vr;
;   };
;   lstore(0, k0, v0); lstore(1, k1, v1);
;   __syncthreads();
.LBB0_325:
	s_mul_i32 s6, s2, 9
	s_lshr_b32 s7, s23, 8
	s_add_i32 s6, s6, s7
	s_mov_b32 s101, s7
	s_lshr_b32 s7, s6, 6
	s_and_b32 s36, s6, 63
	s_mul_i32 s37, s7, 43
	s_lshr_b32 s37, s37, 7
	s_mul_i32 s38, s37, 3
	s_sub_i32 s38, s7, s38
	s_cmp_ge_u32 s37, 6
	s_cselect_b32 s39, 1, 0
	s_mul_i32 s40, s39, 6
	s_sub_i32 s40, s37, s40
	s_lshl_b32 s41, s38, 1
	s_lshr_b32 s42, 0x4000, s41
	s_sub_i32 s43, 6, s41
	s_lshr_b32 s44, s36, s43
	s_lshr_b32 s45, 64, s41
	s_add_i32 s45, s45, -1
	s_and_b32 s45, s36, s45
	s_lshl_b32 s46, s45, 8
	s_min_u32 s100, s101, s45
	s_min_u32 s100, s100, 1
	v_readfirstlane_b32 s47, v224
	v_and_b32_e32 v2, 31, v224
	v_bfe_u32 v3, v224, 5, 1
	v_lshrrev_b32_e32 v12, 3, v224
	v_and_b32_e32 v13, 7, v224
	s_lshr_b32 s47, s47, 6
	s_cmp_eq_u32 s39, 0
	s_cselect_b32 s12, 0, 0x6000000
	s_add_u32 s16, s78, s12
	s_addc_u32 s17, s79, 0
	s_lshl_b32 s12, s40, 7
	s_add_u32 s16, s16, s12
	s_addc_u32 s17, s17, 0
	s_lshl_b32 s12, s47, 5
	s_add_i32 s12, s12, s46
	v_add_u32_e32 v15, s12, v2
	v_lshlrev_b32_e32 v15, s41, v15
	v_add_u32_e32 v15, s44, v15
	v_lshlrev_b32_e32 v0, 4, v3
	v_mov_b32_e32 v186, s16
	v_mov_b32_e32 v187, s17
	v_lshl_add_u64 v[188:189], v[186:187], 0, v[0:1]
	v_mad_u64_u32 v[184:185], s[18:19], v15, s9, v[188:189]
	global_load_dwordx4 v[96:99], v[184:185], off offset:1536
	global_load_dwordx4 v[100:103], v[184:185], off offset:1568
	global_load_dwordx4 v[104:107], v[184:185], off offset:1600
	global_load_dwordx4 v[108:111], v[184:185], off offset:1632
	v_lshlrev_b32_e32 v0, 4, v13
	v_lshl_add_u64 v[10:11], v[186:187], 0, v[0:1]
	s_add_i32 s12, s46, 0xffffffc0
	v_add_u32_e32 v14, s12, v12
	s_add_i32 s18, s42, -1
	s_cmp_eq_u32 s100, 1
	s_cbranch_scc1 .Ldil_have_t01
	v_mov_b32_e32 v0, v14
	v_max_i32_e32 v0, 0, v0
	v_min_i32_e32 v0, s18, v0
	v_lshlrev_b32_e32 v0, s41, v0
	v_add_u32_e32 v0, s44, v0
	v_mad_u64_u32 v[184:185], s[20:21], v0, s9, v[10:11]
	global_load_dwordx4 v[136:139], v[184:185], off offset:2304
	global_load_dwordx4 v[140:143], v[184:185], off offset:3072
	v_add_u32_e32 v0, 64, v14
	v_max_i32_e32 v0, 0, v0
	v_min_i32_e32 v0, s18, v0
	v_lshlrev_b32_e32 v0, s41, v0
	v_add_u32_e32 v0, s44, v0
	v_mad_u64_u32 v[184:185], s[20:21], v0, s9, v[10:11]
	global_load_dwordx4 v[144:147], v[184:185], off offset:2304
	global_load_dwordx4 v[148:151], v[184:185], off offset:3072
.Ldil_have_t01:
	v_add_u32_e32 v0, 128, v14
	v_max_i32_e32 v0, 0, v0
	v_min_i32_e32 v0, s18, v0
	v_lshlrev_b32_e32 v0, s41, v0
	v_add_u32_e32 v0, s44, v0
	v_mad_u64_u32 v[184:185], s[20:21], v0, s9, v[10:11]
	global_load_dwordx4 v[152:155], v[184:185], off offset:2304
	global_load_dwordx4 v[156:159], v[184:185], off offset:3072
	v_add_u32_e32 v0, 192, v14
	v_max_i32_e32 v0, 0, v0
	v_min_i32_e32 v0, s18, v0
	v_lshlrev_b32_e32 v0, s41, v0
	v_add_u32_e32 v0, s44, v0
	v_mad_u64_u32 v[184:185], s[20:21], v0, s9, v[10:11]
	global_load_dwordx4 v[160:163], v[184:185], off offset:2304
	global_load_dwordx4 v[164:167], v[184:185], off offset:3072
	v_add_u32_e32 v0, 256, v14
	v_max_i32_e32 v0, 0, v0
	v_min_i32_e32 v0, s18, v0
	v_lshlrev_b32_e32 v0, s41, v0
	v_add_u32_e32 v0, s44, v0
	v_mad_u64_u32 v[184:185], s[20:21], v0, s9, v[10:11]
	global_load_dwordx4 v[168:171], v[184:185], off offset:2304
	global_load_dwordx4 v[172:175], v[184:185], off offset:3072
	v_add_u32_e32 v0, 320, v14
	v_max_i32_e32 v0, 0, v0
	v_min_i32_e32 v0, s18, v0
	v_lshlrev_b32_e32 v0, s41, v0
	v_add_u32_e32 v0, s44, v0
	v_mad_u64_u32 v[184:185], s[20:21], v0, s9, v[10:11]
	global_load_dwordx4 v[176:179], v[184:185], off offset:2304
	global_load_dwordx4 v[180:183], v[184:185], off offset:3072
	v_mul_u32_u24_e32 v6, 0x90, v12
	v_lshl_add_u32 v6, v13, 4, v6
	v_mul_u32_u24_e32 v7, 0xc0, v12
	v_lshl_add_u32 v7, v13, 4, v7
	v_add_u32_e32 v7, 0x9000, v7
	v_mul_u32_u24_e32 v8, 0x90, v2
	v_lshl_add_u32 v8, v3, 4, v8
	v_bfe_u32 v0, v227, 2, 2
	v_lshl_add_u32 v0, v3, 2, v0
	v_mul_u32_u24_e32 v9, 0xc0, v0
	v_bfe_u32 v0, v227, 4, 1
	v_lshl_add_u32 v9, v0, 5, v9
	v_and_b32_e32 v0, 3, v227
	v_lshl_add_u32 v9, v0, 3, v9
	v_add_u32_e32 v9, 0x9000, v9
	v_lshlrev_b32_e32 v10, 2, v3
	v_sub_u32_e32 v10, v10, v2
	s_lshl_b32 s12, s47, 5
	v_subrev_u32_e32 v10, s12, v10
	v_lshlrev_b32_e32 v11, 2, v3
	s_add_i32 s12, s46, 0xffffffc0
	v_add_u32_e32 v11, s12, v11
	v_xor_b32_e32 v12, 32, v227
	v_lshlrev_b32_e32 v12, 2, v12
	v_mov_b32_e32 v4, 0xe0ad78ec
	v_mov_b32_e32 v5, 0
	v_mov_b32_e32 v32, 0
	v_mov_b32_e32 v33, 0
	v_mov_b32_e32 v34, 0
	v_mov_b32_e32 v35, 0
	v_mov_b32_e32 v36, 0
	v_mov_b32_e32 v37, 0
	v_mov_b32_e32 v38, 0
	v_mov_b32_e32 v39, 0
	v_mov_b32_e32 v40, 0
	v_mov_b32_e32 v41, 0
	v_mov_b32_e32 v42, 0
	v_mov_b32_e32 v43, 0
	v_mov_b32_e32 v44, 0
	v_mov_b32_e32 v45, 0
	v_mov_b32_e32 v46, 0
	v_mov_b32_e32 v47, 0
	v_mov_b32_e32 v48, 0
	v_mov_b32_e32 v49, 0
	v_mov_b32_e32 v50, 0
	v_mov_b32_e32 v51, 0
	v_mov_b32_e32 v52, 0
	v_mov_b32_e32 v53, 0
	v_mov_b32_e32 v54, 0
	v_mov_b32_e32 v55, 0
	v_mov_b32_e32 v56, 0
	v_mov_b32_e32 v57, 0
	v_mov_b32_e32 v58, 0
	v_mov_b32_e32 v59, 0
	v_mov_b32_e32 v60, 0
	v_mov_b32_e32 v61, 0
	v_mov_b32_e32 v62, 0
	v_mov_b32_e32 v63, 0
	s_cmp_eq_u32 s100, 1
	s_cbranch_scc1 .Ldil_stage_pf
	s_waitcnt vmcnt(11)
	ds_write_b128 v6, v[136:139]
	s_waitcnt vmcnt(10)
	ds_write_b128 v7, v[140:143]
	s_waitcnt vmcnt(9)
	ds_write_b128 v6, v[144:147] offset:9216
	s_waitcnt vmcnt(8)
	ds_write_b128 v7, v[148:151] offset:12288
	s_branch .Ldil_staged
.Ldil_stage_pf:
	s_waitcnt vmcnt(8)
.Ldil_staged:
	s_mov_b32 s98, s47
	s_add_i32 s99, s47, 4
	s_waitcnt lgkmcnt(0)
	s_barrier
; #define MFMA32(a, b, c) __builtin_amdgcn_mfma_f32_32x32x16_bf16((a), (b), (c), 0, 0, 0)
; DI float exp2_hw(float x) { return __builtin_amdgcn_exp2f(x); }
; DI void local_softmax_step(float (&sv)[2][16], float& m_run, float& l_run, f32x16 (&O)[2], bf16x8 (&pk)[2][2]) {
;   float tmax = NEGBIG;
; #pragma unroll
;   for (int h2 = 0; h2 < 2; ++h2)
; #pragma unroll
;     for (int i = 0; i < 16; ++i) tmax = fmaxf(tmax, sv[h2][i]);
;   tmax = fmaxf(tmax, __shfl_xor(tmax, 32));
;   const float m_new = fmaxf(m_run, tmax);
;   if (__builtin_amdgcn_ballot_w64(m_new > m_run) != 0ull) {
;     const float alpha = exp2_hw(m_run - m_new);
;     m_run = m_new; l_run *= alpha;
; #pragma unroll
;     for (int mb = 0; mb < 2; ++mb)
; #pragma unroll
;       for (int i = 0; i < 16; ++i) O[mb][i] *= alpha;
;   }
; DI void swin_attn_item(KP p, int item, u16* sm) {
;     ...
;   for (int j = 0; j < 6; ++j) {
;     const int buf = j & 3;
;     const bool half_only = (w & 1) ? (j == jlo) : (j == jlo + 2);
;     if (j >= jlo && j <= jlo + 2 && !half_only) {
;       f32x16 Sc[2];
; #pragma unroll
;       for (int i = 0; i < 16; ++i) { Sc[0][i] = 0.f; Sc[1][i] = 0.f; }
; #pragma unroll
;       for (int s = 0; s < 4; ++s)
; #pragma unroll
;         for (int h2 = 0; h2 < 2; ++h2) {
;           const bf16x8 kf = *(const bf16x8*)(Ks + buf * KS_BUF + (h2 * 32 + r) * KS_STRIDE + s * 16 + 8 * hh);
;           Sc[h2] = MFMA32(kf, qf[s], Sc[h2]);
;         }
;       const int dbase = (64 * j - 32 * w) + 4 * hh - r;
;       const int kbase = P - 64 + 64 * j + 4 * hh;
;       float sv[2][16];
; #pragma unroll
;       for (int h2 = 0; h2 < 2; ++h2)
; #pragma unroll
;         for (int i = 0; i < 16; ++i) {
;           const int c = h2 * 32 + (i & 3) + 8 * (i >> 2);
;           const bool valid = ((unsigned)(dbase + c) <= 128u) && ((unsigned)(kbase + c) < (unsigned)L);
;           sv[h2][i] = valid ? Sc[h2][i] : NEGBIG;
;         }
;       bf16x8 pk[2][2];
;       local_softmax_step(sv, m_run, l_run, O, pk);
; #pragma unroll
;       for (int h2 = 0; h2 < 2; ++h2)
; #pragma unroll
;         for (int sp = 0; sp < 2; ++sp)
; #pragma unroll
;           for (int mb = 0; mb < 2; ++mb) {
;             const bf16x8 vf = v_frag_tr(Vs + buf * VS_BUF, h2 * 32, mb, sp, lane);
;             O[mb] = MFMA32(vf, pk[h2][sp], O[mb]);
;           }
.Ldil_a_top:
	s_cmp_gt_u32 s98, 3
	s_cbranch_scc1 .Ldil_a_done
	s_cmp_gt_u32 s98, s99
	s_cbranch_scc1 .Ldil_a_done
	s_lshr_b32 s16, s98, 1
	s_and_b32 s16, s16, 3
	s_and_b32 s17, s98, 1
	s_mul_i32 s18, s16, 0x2400
	s_mul_i32 s19, s17, 0x1200
	s_add_i32 s18, s18, s19
	s_mul_i32 s19, s16, 0x3000
	s_mul_i32 s20, s17, 0x1800
	s_add_i32 s19, s19, s20
	v_add_u32_e32 v184, s18, v8
	v_add_u32_e32 v185, s19, v9
	ds_read_b128 v[88:91], v184
	ds_read_b128 v[92:95], v184 offset:32
	ds_read_b128 v[112:115], v184 offset:64
	ds_read_b128 v[116:119], v184 offset:96
	ds_read_b64_tr_b16 v[120:121], v185
	ds_read_b64_tr_b16 v[122:123], v185 offset:1536
	ds_read_b64_tr_b16 v[124:125], v185 offset:64
	ds_read_b64_tr_b16 v[126:127], v185 offset:1600
	ds_read_b64_tr_b16 v[128:129], v185 offset:3072
	ds_read_b64_tr_b16 v[130:131], v185 offset:4608
	ds_read_b64_tr_b16 v[132:133], v185 offset:3136
	ds_read_b64_tr_b16 v[134:135], v185 offset:4672
	s_waitcnt lgkmcnt(11)
	v_mfma_f32_32x32x16_bf16 v[64:79], v[88:91], v[96:99], 0
	s_waitcnt lgkmcnt(10)
	v_mfma_f32_32x32x16_bf16 v[64:79], v[92:95], v[100:103], v[64:79]
	s_waitcnt lgkmcnt(9)
	v_mfma_f32_32x32x16_bf16 v[64:79], v[112:115], v[104:107], v[64:79]
	s_waitcnt lgkmcnt(8)
	v_mfma_f32_32x32x16_bf16 v[64:79], v[116:119], v[108:111], v[64:79]
	s_lshl_b32 s16, s98, 5
	v_add_u32_e32 v188, s16, v10
	v_add_u32_e32 v189, s16, v11
	v_min_i32_e32 v0, v188, v189
	v_sub_u32_e32 v0, 0, v0
	v_sub_u32_e32 v188, 0x80, v188
	s_add_i32 s16, s42, -1
	v_sub_u32_e32 v189, s16, v189
	v_min_i32_e32 v14, v188, v189
	v_cmp_lt_i32_e32 vcc, 0, v0
	v_cmp_gt_i32_e64 s[20:21], 27, v14
	s_or_b64 vcc, vcc, s[20:21]
	s_nop 3
	s_cbranch_vccz .Ldil_a_nomask
	v_cmp_ge_i32_e32 vcc, 0, v0
	v_cmp_le_i32_e64 s[20:21], 0, v14
	s_and_b64 vcc, vcc, s[20:21]
	v_cndmask_b32_e32 v64, v240, v64, vcc
	v_cmp_ge_i32_e32 vcc, 1, v0
	v_cmp_le_i32_e64 s[20:21], 1, v14
	s_and_b64 vcc, vcc, s[20:21]
	v_cndmask_b32_e32 v65, v240, v65, vcc
	v_cmp_ge_i32_e32 vcc, 2, v0
	v_cmp_le_i32_e64 s[20:21], 2, v14
	s_and_b64 vcc, vcc, s[20:21]
	v_cndmask_b32_e32 v66, v240, v66, vcc
	v_cmp_ge_i32_e32 vcc, 3, v0
	v_cmp_le_i32_e64 s[20:21], 3, v14
	s_and_b64 vcc, vcc, s[20:21]
	v_cndmask_b32_e32 v67, v240, v67, vcc
	v_cmp_ge_i32_e32 vcc, 8, v0
	v_cmp_le_i32_e64 s[20:21], 8, v14
	s_and_b64 vcc, vcc, s[20:21]
	v_cndmask_b32_e32 v68, v240, v68, vcc
	v_cmp_ge_i32_e32 vcc, 9, v0
	v_cmp_le_i32_e64 s[20:21], 9, v14
	s_and_b64 vcc, vcc, s[20:21]
	v_cndmask_b32_e32 v69, v240, v69, vcc
	v_cmp_ge_i32_e32 vcc, 10, v0
	v_cmp_le_i32_e64 s[20:21], 10, v14
	s_and_b64 vcc, vcc, s[20:21]
	v_cndmask_b32_e32 v70, v240, v70, vcc
	v_cmp_ge_i32_e32 vcc, 11, v0
	v_cmp_le_i32_e64 s[20:21], 11, v14
	s_and_b64 vcc, vcc, s[20:21]
	v_cndmask_b32_e32 v71, v240, v71, vcc
	v_cmp_ge_i32_e32 vcc, 16, v0
	v_cmp_le_i32_e64 s[20:21], 16, v14
	s_and_b64 vcc, vcc, s[20:21]
	v_cndmask_b32_e32 v72, v240, v72, vcc
	v_cmp_ge_i32_e32 vcc, 17, v0
	v_cmp_le_i32_e64 s[20:21], 17, v14
	s_and_b64 vcc, vcc, s[20:21]
	v_cndmask_b32_e32 v73, v240, v73, vcc
	v_cmp_ge_i32_e32 vcc, 18, v0
	v_cmp_le_i32_e64 s[20:21], 18, v14
	s_and_b64 vcc, vcc, s[20:21]
	v_cndmask_b32_e32 v74, v240, v74, vcc
	v_cmp_ge_i32_e32 vcc, 19, v0
	v_cmp_le_i32_e64 s[20:21], 19, v14
	s_and_b64 vcc, vcc, s[20:21]
	v_cndmask_b32_e32 v75, v240, v75, vcc
	v_cmp_ge_i32_e32 vcc, 24, v0
	v_cmp_le_i32_e64 s[20:21], 24, v14
	s_and_b64 vcc, vcc, s[20:21]
	v_cndmask_b32_e32 v76, v240, v76, vcc
	v_cmp_ge_i32_e32 vcc, 25, v0
	v_cmp_le_i32_e64 s[20:21], 25, v14
	s_and_b64 vcc, vcc, s[20:21]
	v_cndmask_b32_e32 v77, v240, v77, vcc
	v_cmp_ge_i32_e32 vcc, 26, v0
	v_cmp_le_i32_e64 s[20:21], 26, v14
	s_and_b64 vcc, vcc, s[20:21]
	v_cndmask_b32_e32 v78, v240, v78, vcc
	v_cmp_ge_i32_e32 vcc, 27, v0
	v_cmp_le_i32_e64 s[20:21], 27, v14
	s_and_b64 vcc, vcc, s[20:21]
	v_cndmask_b32_e32 v79, v240, v79, vcc
.Ldil_a_nomask:
	v_max3_f32 v0, v64, v65, v66
	v_max3_f32 v0, v0, v67, v68
	v_max3_f32 v0, v0, v69, v70
	v_max3_f32 v0, v0, v71, v72
	v_max3_f32 v0, v0, v73, v74
	v_max3_f32 v0, v0, v75, v76
	v_max3_f32 v0, v0, v77, v78
	v_max_f32_e32 v0, v0, v79
	s_nop 0
	ds_bpermute_b32 v14, v12, v0
	s_waitcnt lgkmcnt(0)
	v_max3_f32 v14, v4, v0, v14
	v_cmp_gt_f32_e32 vcc, v14, v4
	s_nop 4
	s_cbranch_vccz .Ldil_a_noresc
	v_sub_f32_e32 v0, v4, v14
	v_exp_f32_e32 v0, v0
	v_mov_b32_e32 v4, v14
	s_nop 0
	v_mul_f32_e32 v5, v5, v0
	v_mul_f32_e32 v32, v32, v0
	v_mul_f32_e32 v33, v33, v0
	v_mul_f32_e32 v34, v34, v0
	v_mul_f32_e32 v35, v35, v0
	v_mul_f32_e32 v36, v36, v0
	v_mul_f32_e32 v37, v37, v0
	v_mul_f32_e32 v38, v38, v0
	v_mul_f32_e32 v39, v39, v0
	v_mul_f32_e32 v40, v40, v0
	v_mul_f32_e32 v41, v41, v0
	v_mul_f32_e32 v42, v42, v0
	v_mul_f32_e32 v43, v43, v0
	v_mul_f32_e32 v44, v44, v0
	v_mul_f32_e32 v45, v45, v0
	v_mul_f32_e32 v46, v46, v0
	v_mul_f32_e32 v47, v47, v0
	v_mul_f32_e32 v48, v48, v0
	v_mul_f32_e32 v49, v49, v0
	v_mul_f32_e32 v50, v50, v0
	v_mul_f32_e32 v51, v51, v0
	v_mul_f32_e32 v52, v52, v0
	v_mul_f32_e32 v53, v53, v0
	v_mul_f32_e32 v54, v54, v0
	v_mul_f32_e32 v55, v55, v0
	v_mul_f32_e32 v56, v56, v0
	v_mul_f32_e32 v57, v57, v0
	v_mul_f32_e32 v58, v58, v0
	v_mul_f32_e32 v59, v59, v0
	v_mul_f32_e32 v60, v60, v0
	v_mul_f32_e32 v61, v61, v0
	v_mul_f32_e32 v62, v62, v0
	v_mul_f32_e32 v63, v63, v0
; #define MFMA32(a, b, c) __builtin_amdgcn_mfma_f32_32x32x16_bf16((a), (b), (c), 0, 0, 0)
; DI void local_softmax_step(float (&sv)[2][16], float& m_run, float& l_run, f32x16 (&O)[2], bf16x8 (&pk)[2][2]) {
;     ...
; #pragma unroll
;   for (int h2 = 0; h2 < 2; ++h2)
; #pragma unroll
;     for (int sp = 0; sp < 2; ++sp) {
;       unsigned q4[4];
; #pragma unroll
;       for (int q = 0; q < 4; ++q) {
;         const float s0 = sv[h2][8 * sp + 2 * q], s1 = sv[h2][8 * sp + 2 * q + 1];
;         const float p0 = exp2_hw(s0 - m_run), p1 = exp2_hw(s1 - m_run);
;         l_run += p0; l_run += p1;
;         q4[q] = pack2(p0, p1);
;       }
;       pk[h2][sp] = __builtin_bit_cast(bf16x8, make_uint4(q4[0], q4[1], q4[2], q4[3]));
;     }
; }
; DI void swin_attn_item(KP p, int item, u16* sm) {
;     ...
; #pragma unroll
;       for (int h2 = 0; h2 < 2; ++h2)
; #pragma unroll
;         for (int sp = 0; sp < 2; ++sp)
; #pragma unroll
;           for (int mb = 0; mb < 2; ++mb) {
;             const bf16x8 vf = v_frag_tr(Vs + buf * VS_BUF, h2 * 32, mb, sp, lane);
;             O[mb] = MFMA32(vf, pk[h2][sp], O[mb]);
;           }
;     } else if (j >= jlo && j <= jlo + 2) {
;       const int hs = (w & 1) * 32;
;       f32x16 Sc;
; #pragma unroll
;       for (int i = 0; i < 16; ++i) Sc[i] = 0.f;
; #pragma unroll
;       for (int s = 0; s < 4; ++s) {
;         const bf16x8 kf = *(const bf16x8*)(Ks + buf * KS_BUF + (hs + r) * KS_STRIDE + s * 16 + 8 * hh);
;         Sc = MFMA32(kf, qf[s], Sc);
;       }
;       const int dbase = (64 * j - 32 * w) + hs + 4 * hh - r;
;       const int kbase = P - 64 + 64 * j + hs + 4 * hh;
;       float sv[16];
; #pragma unroll
;       for (int i = 0; i < 16; ++i) {
;         const int c = (i & 3) + 8 * (i >> 2);
;         const bool valid = ((unsigned)(dbase + c) <= 128u) && ((unsigned)(kbase + c) < (unsigned)L);
;         sv[i] = valid ? Sc[i] : NEGBIG;
;       }
;       bf16x8 pk[2];
;       local_softmax_step1(sv, m_run, l_run, O, pk);
; #pragma unroll
;       for (int sp = 0; sp < 2; ++sp)
; #pragma unroll
;         for (int mb = 0; mb < 2; ++mb) {
;           const bf16x8 vf = v_frag_tr(Vs + buf * VS_BUF, hs, mb, sp, lane);
;           O[mb] = MFMA32(vf, pk[sp], O[mb]);
;         }
;     }
;     if (j == 1) { lstore(2, k2, v2); lstore(3, k3, v3); __syncthreads(); }
;     if (j == 3) { lstore(0, k4, v4); lstore(1, k5, v5); __syncthreads(); }
.Ldil_a_noresc:
	v_sub_f32_e32 v64, v64, v4
	v_sub_f32_e32 v65, v65, v4
	v_sub_f32_e32 v66, v66, v4
	v_sub_f32_e32 v67, v67, v4
	v_sub_f32_e32 v68, v68, v4
	v_sub_f32_e32 v69, v69, v4
	v_sub_f32_e32 v70, v70, v4
	v_sub_f32_e32 v71, v71, v4
	v_sub_f32_e32 v72, v72, v4
	v_sub_f32_e32 v73, v73, v4
	v_sub_f32_e32 v74, v74, v4
	v_sub_f32_e32 v75, v75, v4
	v_sub_f32_e32 v76, v76, v4
	v_sub_f32_e32 v77, v77, v4
	v_sub_f32_e32 v78, v78, v4
	v_sub_f32_e32 v79, v79, v4
	v_exp_f32_e32 v64, v64
	v_exp_f32_e32 v65, v65
	v_exp_f32_e32 v66, v66
	v_exp_f32_e32 v67, v67
	v_exp_f32_e32 v68, v68
	v_exp_f32_e32 v69, v69
	v_exp_f32_e32 v70, v70
	v_exp_f32_e32 v71, v71
	v_exp_f32_e32 v72, v72
	v_exp_f32_e32 v73, v73
	v_exp_f32_e32 v74, v74
	v_exp_f32_e32 v75, v75
	v_exp_f32_e32 v76, v76
	v_exp_f32_e32 v77, v77
	v_exp_f32_e32 v78, v78
	v_exp_f32_e32 v79, v79
	s_nop 0
	v_add_f32_e32 v0, v64, v65
	v_add_f32_e32 v14, v66, v67
	v_add_f32_e32 v0, v0, v68
	v_add_f32_e32 v14, v14, v69
	v_add_f32_e32 v0, v0, v70
	v_add_f32_e32 v14, v14, v71
	v_add_f32_e32 v0, v0, v72
	v_add_f32_e32 v14, v14, v73
	v_add_f32_e32 v0, v0, v74
	v_add_f32_e32 v14, v14, v75
	v_add_f32_e32 v0, v0, v76
	v_add_f32_e32 v14, v14, v77
	v_add_f32_e32 v0, v0, v78
	v_add_f32_e32 v14, v14, v79
	v_add_f32_e32 v0, v0, v14
	v_add_f32_e32 v5, v5, v0
	v_cvt_pk_bf16_f32 v80, v64, v65
	v_cvt_pk_bf16_f32 v81, v66, v67
	v_cvt_pk_bf16_f32 v82, v68, v69
	v_cvt_pk_bf16_f32 v83, v70, v71
	v_cvt_pk_bf16_f32 v84, v72, v73
	v_cvt_pk_bf16_f32 v85, v74, v75
	v_cvt_pk_bf16_f32 v86, v76, v77
	v_cvt_pk_bf16_f32 v87, v78, v79
	s_nop 1
	v_mfma_f32_32x32x16_bf16 v[32:47], v[120:123], v[80:83], v[32:47]
	v_mfma_f32_32x32x16_bf16 v[48:63], v[124:127], v[80:83], v[48:63]
	v_mfma_f32_32x32x16_bf16 v[32:47], v[128:131], v[84:87], v[32:47]
	v_mfma_f32_32x32x16_bf16 v[48:63], v[132:135], v[84:87], v[48:63]
	s_add_i32 s98, s98, 1
	s_branch .Ldil_a_top
.Ldil_a_done:
	s_waitcnt vmcnt(7)
	ds_write_b128 v6, v[152:155] offset:18432
	s_waitcnt vmcnt(6)
	ds_write_b128 v7, v[156:159] offset:24576
	s_waitcnt vmcnt(5)
	ds_write_b128 v6, v[160:163] offset:27648
	s_waitcnt vmcnt(4)
	ds_write_b128 v7, v[164:167] offset:36864
	s_waitcnt lgkmcnt(0)
	s_barrier
.Ldil_b_top:
	s_cmp_gt_u32 s98, 7
	s_cbranch_scc1 .Ldil_b_done
	s_cmp_gt_u32 s98, s99
	s_cbranch_scc1 .Ldil_b_done
	s_lshr_b32 s16, s98, 1
	s_and_b32 s16, s16, 3
	s_and_b32 s17, s98, 1
	s_mul_i32 s18, s16, 0x2400
	s_mul_i32 s19, s17, 0x1200
	s_add_i32 s18, s18, s19
	s_mul_i32 s19, s16, 0x3000
	s_mul_i32 s20, s17, 0x1800
	s_add_i32 s19, s19, s20
	v_add_u32_e32 v184, s18, v8
	v_add_u32_e32 v185, s19, v9
	ds_read_b128 v[88:91], v184
	ds_read_b128 v[92:95], v184 offset:32
	ds_read_b128 v[112:115], v184 offset:64
	ds_read_b128 v[116:119], v184 offset:96
	ds_read_b64_tr_b16 v[120:121], v185
	ds_read_b64_tr_b16 v[122:123], v185 offset:1536
	ds_read_b64_tr_b16 v[124:125], v185 offset:64
	ds_read_b64_tr_b16 v[126:127], v185 offset:1600
	ds_read_b64_tr_b16 v[128:129], v185 offset:3072
	ds_read_b64_tr_b16 v[130:131], v185 offset:4608
	ds_read_b64_tr_b16 v[132:133], v185 offset:3136
	ds_read_b64_tr_b16 v[134:135], v185 offset:4672
	s_waitcnt lgkmcnt(11)
	v_mfma_f32_32x32x16_bf16 v[64:79], v[88:91], v[96:99], 0
	s_waitcnt lgkmcnt(10)
	v_mfma_f32_32x32x16_bf16 v[64:79], v[92:95], v[100:103], v[64:79]
	s_waitcnt lgkmcnt(9)
	v_mfma_f32_32x32x16_bf16 v[64:79], v[112:115], v[104:107], v[64:79]
	s_waitcnt lgkmcnt(8)
	v_mfma_f32_32x32x16_bf16 v[64:79], v[116:119], v[108:111], v[64:79]
	s_lshl_b32 s16, s98, 5
	v_add_u32_e32 v188, s16, v10
	v_add_u32_e32 v189, s16, v11
	v_min_i32_e32 v0, v188, v189
	v_sub_u32_e32 v0, 0, v0
	v_sub_u32_e32 v188, 0x80, v188
	s_add_i32 s16, s42, -1
	v_sub_u32_e32 v189, s16, v189
	v_min_i32_e32 v14, v188, v189
	v_cmp_lt_i32_e32 vcc, 0, v0
	v_cmp_gt_i32_e64 s[20:21], 27, v14
	s_or_b64 vcc, vcc, s[20:21]
	s_nop 3
	s_cbranch_vccz .Ldil_b_nomask
	v_cmp_ge_i32_e32 vcc, 0, v0
	v_cmp_le_i32_e64 s[20:21], 0, v14
	s_and_b64 vcc, vcc, s[20:21]
	v_cndmask_b32_e32 v64, v240, v64, vcc
	v_cmp_ge_i32_e32 vcc, 1, v0
	v_cmp_le_i32_e64 s[20:21], 1, v14
	s_and_b64 vcc, vcc, s[20:21]
	v_cndmask_b32_e32 v65, v240, v65, vcc
	v_cmp_ge_i32_e32 vcc, 2, v0
	v_cmp_le_i32_e64 s[20:21], 2, v14
	s_and_b64 vcc, vcc, s[20:21]
	v_cndmask_b32_e32 v66, v240, v66, vcc
	v_cmp_ge_i32_e32 vcc, 3, v0
	v_cmp_le_i32_e64 s[20:21], 3, v14
	s_and_b64 vcc, vcc, s[20:21]
	v_cndmask_b32_e32 v67, v240, v67, vcc
	v_cmp_ge_i32_e32 vcc, 8, v0
	v_cmp_le_i32_e64 s[20:21], 8, v14
	s_and_b64 vcc, vcc, s[20:21]
	v_cndmask_b32_e32 v68, v240, v68, vcc
	v_cmp_ge_i32_e32 vcc, 9, v0
	v_cmp_le_i32_e64 s[20:21], 9, v14
	s_and_b64 vcc, vcc, s[20:21]
	v_cndmask_b32_e32 v69, v240, v69, vcc
	v_cmp_ge_i32_e32 vcc, 10, v0
	v_cmp_le_i32_e64 s[20:21], 10, v14
	s_and_b64 vcc, vcc, s[20:21]
	v_cndmask_b32_e32 v70, v240, v70, vcc
	v_cmp_ge_i32_e32 vcc, 11, v0
	v_cmp_le_i32_e64 s[20:21], 11, v14
	s_and_b64 vcc, vcc, s[20:21]
	v_cndmask_b32_e32 v71, v240, v71, vcc
	v_cmp_ge_i32_e32 vcc, 16, v0
	v_cmp_le_i32_e64 s[20:21], 16, v14
	s_and_b64 vcc, vcc, s[20:21]
	v_cndmask_b32_e32 v72, v240, v72, vcc
	v_cmp_ge_i32_e32 vcc, 17, v0
	v_cmp_le_i32_e64 s[20:21], 17, v14
	s_and_b64 vcc, vcc, s[20:21]
	v_cndmask_b32_e32 v73, v240, v73, vcc
	v_cmp_ge_i32_e32 vcc, 18, v0
	v_cmp_le_i32_e64 s[20:21], 18, v14
	s_and_b64 vcc, vcc, s[20:21]
	v_cndmask_b32_e32 v74, v240, v74, vcc
	v_cmp_ge_i32_e32 vcc, 19, v0
	v_cmp_le_i32_e64 s[20:21], 19, v14
	s_and_b64 vcc, vcc, s[20:21]
	v_cndmask_b32_e32 v75, v240, v75, vcc
	v_cmp_ge_i32_e32 vcc, 24, v0
	v_cmp_le_i32_e64 s[20:21], 24, v14
	s_and_b64 vcc, vcc, s[20:21]
	v_cndmask_b32_e32 v76, v240, v76, vcc
	v_cmp_ge_i32_e32 vcc, 25, v0
	v_cmp_le_i32_e64 s[20:21], 25, v14
	s_and_b64 vcc, vcc, s[20:21]
	v_cndmask_b32_e32 v77, v240, v77, vcc
	v_cmp_ge_i32_e32 vcc, 26, v0
	v_cmp_le_i32_e64 s[20:21], 26, v14
	s_and_b64 vcc, vcc, s[20:21]
	v_cndmask_b32_e32 v78, v240, v78, vcc
	v_cmp_ge_i32_e32 vcc, 27, v0
	v_cmp_le_i32_e64 s[20:21], 27, v14
	s_and_b64 vcc, vcc, s[20:21]
	v_cndmask_b32_e32 v79, v240, v79, vcc

; #define MFMA32(a, b, c) __builtin_amdgcn_mfma_f32_32x32x16_bf16((a), (b), (c), 0, 0, 0)
; DI void swin_attn_item(KP p, int item, u16* sm) {
;     ...
;   for (int j = 0; j < 6; ++j) {
;     const int buf = j & 3;
;     const bool half_only = (w & 1) ? (j == jlo) : (j == jlo + 2);
;     if (j >= jlo && j <= jlo + 2 && !half_only) {
;       f32x16 Sc[2];
; #pragma unroll
;       for (int i = 0; i < 16; ++i) { Sc[0][i] = 0.f; Sc[1][i] = 0.f; }
; #pragma unroll
;       for (int s = 0; s < 4; ++s)
; #pragma unroll
;         for (int h2 = 0; h2 < 2; ++h2) {
;           const bf16x8 kf = *(const bf16x8*)(Ks + buf * KS_BUF + (h2 * 32 + r) * KS_STRIDE + s * 16 + 8 * hh);
;           Sc[h2] = MFMA32(kf, qf[s], Sc[h2]);
;         }
;       const int dbase = (64 * j - 32 * w) + 4 * hh - r;
;       const int kbase = P - 64 + 64 * j + 4 * hh;
;       float sv[2][16];
; #pragma unroll
;       for (int h2 = 0; h2 < 2; ++h2)
; #pragma unroll
;         for (int i = 0; i < 16; ++i) {
;           const int c = h2 * 32 + (i & 3) + 8 * (i >> 2);
;           const bool valid = ((unsigned)(dbase + c) <= 128u) && ((unsigned)(kbase + c) < (unsigned)L);
;           sv[h2][i] = valid ? Sc[h2][i] : NEGBIG;
;         }
;     ...
;     if (j == 1) { lstore(2, k2, v2); lstore(3, k3, v3); __syncthreads(); }
;     if (j == 3) { lstore(0, k4, v4); lstore(1, k5, v5); __syncthreads(); }
.Ldil_b_done:
	s_waitcnt vmcnt(3)
	ds_write_b128 v6, v[168:171]
	s_waitcnt vmcnt(2)
	ds_write_b128 v7, v[172:175]
	s_waitcnt vmcnt(1)
	ds_write_b128 v6, v[176:179] offset:9216
	s_waitcnt vmcnt(0)
	ds_write_b128 v7, v[180:183] offset:12288
	s_waitcnt lgkmcnt(0)
	s_barrier
.Ldil_c_top:
	s_cmp_gt_u32 s98, 11
	s_cbranch_scc1 .Ldil_c_done
	s_cmp_gt_u32 s98, s99
	s_cbranch_scc1 .Ldil_c_done
	s_lshr_b32 s16, s98, 1
	s_and_b32 s16, s16, 3
	s_and_b32 s17, s98, 1
	s_mul_i32 s18, s16, 0x2400
	s_mul_i32 s19, s17, 0x1200
	s_add_i32 s18, s18, s19
	s_mul_i32 s19, s16, 0x3000
	s_mul_i32 s20, s17, 0x1800
	s_add_i32 s19, s19, s20
	v_add_u32_e32 v184, s18, v8
	v_add_u32_e32 v185, s19, v9
	ds_read_b128 v[88:91], v184
	ds_read_b128 v[92:95], v184 offset:32
	ds_read_b128 v[112:115], v184 offset:64
	ds_read_b128 v[116:119], v184 offset:96
	ds_read_b64_tr_b16 v[120:121], v185
	ds_read_b64_tr_b16 v[122:123], v185 offset:1536
	ds_read_b64_tr_b16 v[124:125], v185 offset:64
	ds_read_b64_tr_b16 v[126:127], v185 offset:1600
	ds_read_b64_tr_b16 v[128:129], v185 offset:3072
	ds_read_b64_tr_b16 v[130:131], v185 offset:4608
	ds_read_b64_tr_b16 v[132:133], v185 offset:3136
	ds_read_b64_tr_b16 v[134:135], v185 offset:4672
	s_waitcnt lgkmcnt(11)
	v_mfma_f32_32x32x16_bf16 v[64:79], v[88:91], v[96:99], 0
	s_waitcnt lgkmcnt(10)
	v_mfma_f32_32x32x16_bf16 v[64:79], v[92:95], v[100:103], v[64:79]
	s_waitcnt lgkmcnt(9)
	v_mfma_f32_32x32x16_bf16 v[64:79], v[112:115], v[104:107], v[64:79]
	s_waitcnt lgkmcnt(8)
	v_mfma_f32_32x32x16_bf16 v[64:79], v[116:119], v[108:111], v[64:79]
	s_lshl_b32 s16, s98, 5
	v_add_u32_e32 v188, s16, v10
	v_add_u32_e32 v189, s16, v11
	v_min_i32_e32 v0, v188, v189
	v_sub_u32_e32 v0, 0, v0
	v_sub_u32_e32 v188, 0x80, v188
	s_add_i32 s16, s42, -1
	v_sub_u32_e32 v189, s16, v189
	v_min_i32_e32 v14, v188, v189
	v_cmp_lt_i32_e32 vcc, 0, v0
	v_cmp_gt_i32_e64 s[20:21], 27, v14
	s_or_b64 vcc, vcc, s[20:21]
	s_nop 3
	s_cbranch_vccz .Ldil_c_nomask
	v_cmp_ge_i32_e32 vcc, 0, v0
	v_cmp_le_i32_e64 s[20:21], 0, v14
	s_and_b64 vcc, vcc, s[20:21]
	v_cndmask_b32_e32 v64, v240, v64, vcc
	v_cmp_ge_i32_e32 vcc, 1, v0
	v_cmp_le_i32_e64 s[20:21], 1, v14
	s_and_b64 vcc, vcc, s[20:21]
	v_cndmask_b32_e32 v65, v240, v65, vcc
	v_cmp_ge_i32_e32 vcc, 2, v0
	v_cmp_le_i32_e64 s[20:21], 2, v14
	s_and_b64 vcc, vcc, s[20:21]
	v_cndmask_b32_e32 v66, v240, v66, vcc
	v_cmp_ge_i32_e32 vcc, 3, v0
	v_cmp_le_i32_e64 s[20:21], 3, v14
	s_and_b64 vcc, vcc, s[20:21]
	v_cndmask_b32_e32 v67, v240, v67, vcc
	v_cmp_ge_i32_e32 vcc, 8, v0
	v_cmp_le_i32_e64 s[20:21], 8, v14
	s_and_b64 vcc, vcc, s[20:21]
	v_cndmask_b32_e32 v68, v240, v68, vcc
	v_cmp_ge_i32_e32 vcc, 9, v0
	v_cmp_le_i32_e64 s[20:21], 9, v14
	s_and_b64 vcc, vcc, s[20:21]
	v_cndmask_b32_e32 v69, v240, v69, vcc
	v_cmp_ge_i32_e32 vcc, 10, v0
	v_cmp_le_i32_e64 s[20:21], 10, v14
	s_and_b64 vcc, vcc, s[20:21]
	v_cndmask_b32_e32 v70, v240, v70, vcc
	v_cmp_ge_i32_e32 vcc, 11, v0
	v_cmp_le_i32_e64 s[20:21], 11, v14
	s_and_b64 vcc, vcc, s[20:21]
	v_cndmask_b32_e32 v71, v240, v71, vcc
	v_cmp_ge_i32_e32 vcc, 16, v0
	v_cmp_le_i32_e64 s[20:21], 16, v14
	s_and_b64 vcc, vcc, s[20:21]
	v_cndmask_b32_e32 v72, v240, v72, vcc
	v_cmp_ge_i32_e32 vcc, 17, v0
	v_cmp_le_i32_e64 s[20:21], 17, v14
	s_and_b64 vcc, vcc, s[20:21]
	v_cndmask_b32_e32 v73, v240, v73, vcc
	v_cmp_ge_i32_e32 vcc, 18, v0
	v_cmp_le_i32_e64 s[20:21], 18, v14
	s_and_b64 vcc, vcc, s[20:21]
	v_cndmask_b32_e32 v74, v240, v74, vcc
	v_cmp_ge_i32_e32 vcc, 19, v0
	v_cmp_le_i32_e64 s[20:21], 19, v14
	s_and_b64 vcc, vcc, s[20:21]
	v_cndmask_b32_e32 v75, v240, v75, vcc
	v_cmp_ge_i32_e32 vcc, 24, v0
	v_cmp_le_i32_e64 s[20:21], 24, v14
	s_and_b64 vcc, vcc, s[20:21]
	v_cndmask_b32_e32 v76, v240, v76, vcc
	v_cmp_ge_i32_e32 vcc, 25, v0
	v_cmp_le_i32_e64 s[20:21], 25, v14
	s_and_b64 vcc, vcc, s[20:21]
	v_cndmask_b32_e32 v77, v240, v77, vcc
	v_cmp_ge_i32_e32 vcc, 26, v0
	v_cmp_le_i32_e64 s[20:21], 26, v14
	s_and_b64 vcc, vcc, s[20:21]
	v_cndmask_b32_e32 v78, v240, v78, vcc
	v_cmp_ge_i32_e32 vcc, 27, v0
	v_cmp_le_i32_e64 s[20:21], 27, v14
	s_and_b64 vcc, vcc, s[20:21]
	v_cndmask_b32_e32 v79, v240, v79, vcc

; DI unsigned pack2(float a, float b) { f2_t v = {a, b}; return __builtin_bit_cast(unsigned, __builtin_convertvector(v, bf2_t)); }
; DI void local_store_out(const f32x16 (&O)[2], float l_run, u16* op, int hh) {
;   const float l = l_run + __shfl_xor(l_run, 32);
;   const float il = 1.f / l;
; #pragma unroll
;   for (int mb = 0; mb < 2; ++mb)
; #pragma unroll
;     for (int g = 0; g < 4; ++g) {
;       const int d = mb * 32 + 8 * g + 4 * hh;
;       *(uint2*)(op + d) = make_uint2(pack2(O[mb][4 * g] * il, O[mb][4 * g + 1] * il), pack2(O[mb][4 * g + 2] * il, O[mb][4 * g + 3] * il));
;     }
; DI void swin_attn_item(KP p, int item, u16* sm) {
;     ...
;   const size_t orow = (size_t)pat * NTOK + (size_t)b * S + tq;
;   const float l = l_run + __shfl_xor(l_run, 32);
;   if (hh == 0) p.lse[orow * 6 + head] = m_run + __log2f(l);
;   local_store_out(O, l_run, p.odil + orow * 384 + head * 64, hh);
.Ldil_c_done:
	s_nop 7
	ds_bpermute_b32 v0, v12, v5
	s_lshl_b32 s12, s38, 15
	s_lshl_b32 s16, s39, 14
	s_add_i32 s12, s12, s16
	v_add_u32_e32 v15, s12, v15
	s_waitcnt lgkmcnt(0)
	v_add_f32_e32 v5, v5, v0
	v_log_f32_e32 v14, v5
	v_mov_b32_e32 v186, s30
	v_mov_b32_e32 v187, s31
	v_mad_u64_u32 v[188:189], s[18:19], v15, 24, v[186:187]
	s_lshl_b32 s12, s40, 2
	v_lshl_add_u64 v[188:189], v[188:189], 0, s[12:13]
	v_add_f32_e32 v14, v4, v14
	v_cmp_eq_u32_e32 vcc, 0, v3
	s_and_saveexec_b64 s[20:21], vcc
	global_store_dword v[188:189], v14, off
	s_mov_b64 exec, s[20:21]
	v_div_scale_f32 v184, s[18:19], v5, v5, 1.0
	v_rcp_f32_e32 v185, v184
	s_nop 0
	v_fma_f32 v188, -v184, v185, 1.0
	v_fmac_f32_e32 v185, v188, v185
	v_div_scale_f32 v188, vcc, 1.0, v5, 1.0
	v_mul_f32_e32 v189, v188, v185
	v_fma_f32 v0, -v184, v189, v188
	v_fmac_f32_e32 v189, v0, v185
	v_fma_f32 v184, -v184, v189, v188
	v_div_fmas_f32 v184, v184, v185, v189
	v_div_fixup_f32 v0, v184, v5, 1.0
	v_mov_b32_e32 v186, s34
	v_mov_b32_e32 v187, s35
	s_movk_i32 s12, 0x300
	v_mad_u64_u32 v[188:189], s[18:19], v15, s12, v[186:187]
	s_lshl_b32 s12, s40, 7
	v_lshl_add_u64 v[188:189], v[188:189], 0, s[12:13]
	v_lshlrev_b32_e32 v186, 3, v3
	v_mov_b32_e32 v187, 0
	v_lshl_add_u64 v[188:189], v[188:189], 0, v[186:187]
	v_mul_f32_e32 v32, v32, v0
	v_mul_f32_e32 v33, v33, v0
	v_mul_f32_e32 v34, v34, v0
	v_mul_f32_e32 v35, v35, v0
	v_mul_f32_e32 v36, v36, v0
	v_mul_f32_e32 v37, v37, v0
	v_mul_f32_e32 v38, v38, v0
	v_mul_f32_e32 v39, v39, v0
	v_mul_f32_e32 v40, v40, v0
	v_mul_f32_e32 v41, v41, v0
	v_mul_f32_e32 v42, v42, v0
	v_mul_f32_e32 v43, v43, v0
	v_mul_f32_e32 v44, v44, v0
	v_mul_f32_e32 v45, v45, v0
	v_mul_f32_e32 v46, v46, v0
	v_mul_f32_e32 v47, v47, v0
	v_mul_f32_e32 v48, v48, v0
	v_mul_f32_e32 v49, v49, v0
	v_mul_f32_e32 v50, v50, v0
	v_mul_f32_e32 v51, v51, v0
	v_mul_f32_e32 v52, v52, v0
	v_mul_f32_e32 v53, v53, v0
	v_mul_f32_e32 v54, v54, v0
	v_mul_f32_e32 v55, v55, v0
	v_mul_f32_e32 v56, v56, v0
	v_mul_f32_e32 v57, v57, v0
	v_mul_f32_e32 v58, v58, v0
	v_mul_f32_e32 v59, v59, v0
	v_mul_f32_e32 v60, v60, v0
	v_mul_f32_e32 v61, v61, v0
	v_mul_f32_e32 v62, v62, v0
	v_mul_f32_e32 v63, v63, v0
	v_cvt_pk_bf16_f32 v64, v32, v33
	v_cvt_pk_bf16_f32 v65, v34, v35
	v_cvt_pk_bf16_f32 v66, v36, v37
	v_cvt_pk_bf16_f32 v67, v38, v39
	v_cvt_pk_bf16_f32 v68, v40, v41
	v_cvt_pk_bf16_f32 v69, v42, v43
	v_cvt_pk_bf16_f32 v70, v44, v45
	v_cvt_pk_bf16_f32 v71, v46, v47
	v_cvt_pk_bf16_f32 v72, v48, v49
	v_cvt_pk_bf16_f32 v73, v50, v51
	v_cvt_pk_bf16_f32 v74, v52, v53
	v_cvt_pk_bf16_f32 v75, v54, v55
	v_cvt_pk_bf16_f32 v76, v56, v57
	v_cvt_pk_bf16_f32 v77, v58, v59
	v_cvt_pk_bf16_f32 v78, v60, v61
	v_cvt_pk_bf16_f32 v79, v62, v63
	global_store_dwordx2 v[188:189], v[64:65], off
	global_store_dwordx2 v[188:189], v[66:67], off offset:16
	global_store_dwordx2 v[188:189], v[68:69], off offset:32
	global_store_dwordx2 v[188:189], v[70:71], off offset:48
	global_store_dwordx2 v[188:189], v[72:73], off offset:64
	global_store_dwordx2 v[188:189], v[74:75], off offset:80
	global_store_dwordx2 v[188:189], v[76:77], off offset:96
	global_store_dwordx2 v[188:189], v[78:79], off offset:112
	s_branch .LBB0_263
